# attention unit prologue: defer rope-fragment LDS writes until after tile-0 DMA issue so Q-load and DMA latencies overlap
# baseline (speedup 1.0000x reference)
.LBB0_1228:
	s_and_b64 s[18:19], s[44:45], exec
	s_cselect_b32 s35, s82, s81
	s_lshl_b32 s34, s35, 8
	s_lshl_b32 s86, s85, 5
	v_and_b32_e32 v227, 31, v220
	s_add_i32 s86, s86, s34
	v_lshrrev_b32_e32 v0, 5, v219
	v_or_b32_e32 v228, s86, v227
	v_mov_b64_e32 v[2:3], s[4:5]
	s_movk_i32 s18, 0x1800
	v_lshlrev_b32_e32 v214, 4, v0
	v_mad_i64_i32 v[2:3], s[18:19], v228, s18, v[2:3]
	v_lshl_add_u64 v[18:19], v[2:3], 0, v[214:215]
	global_load_dwordx4 v[80:83], v[18:19], off
	global_load_dwordx4 v[84:87], v[18:19], off offset:32
	global_load_dwordx4 v[88:91], v[18:19], off offset:64
	global_load_dwordx4 v[92:95], v[18:19], off offset:96
	global_load_dwordx4 v[96:99], v[18:19], off offset:128
	global_load_dwordx4 v[100:103], v[18:19], off offset:160
	global_load_dwordx4 v[2:5], v[18:19], off offset:256
	global_load_dwordx4 v[6:9], v[18:19], off offset:288
	global_load_dwordx4 v[10:13], v[18:19], off offset:320
	global_load_dwordx4 v[14:17], v[18:19], off offset:352
	global_load_dwordx4 v[104:107], v[18:19], off offset:192
	global_load_dwordx4 v[108:111], v[18:19], off offset:224
	s_mul_i32 s18, s85, 0x1200
	s_add_i32 s18, s18, 0
	s_add_i32 s18, s18, 0x16000
	s_movk_i32 s19, 0x90
	v_mov_b32_e32 v1, s18
	v_mad_u32_u24 v1, v227, s19, v1
	s_cmp_lt_i32 s85, 44
	v_add_u32_e32 v1, v1, v214
	s_cselect_b64 s[18:19], -1, 0
	s_cmp_gt_i32 s85, 43
	s_cbranch_scc1 .LBB0_1231
	s_and_b64 vcc, exec, s[16:17]
	s_cbranch_vccz .LBB0_1234
	s_cmp_lt_u32 s85, 26
	s_cselect_b64 s[16:17], -1, 0
	s_lshl_b32 s20, s85, 10
	s_add_i32 s21, s20, 0x6800
	s_and_b64 s[16:17], s[16:17], exec
	s_cselect_b32 s50, s20, s21
	s_cselect_b32 s17, s74, s38
	s_cselect_b32 s16, s73, s37
	s_cbranch_execz .LBB0_1235
	s_branch .LBB0_1236

.LBB0_1264:
	s_lshl_b32 s87, s35, 2
	s_xor_b64 s[16:17], s[44:45], -1
	s_add_i32 s87, s87, 4
	s_ashr_i32 s89, s86, 6
	s_movk_i32 s35, 0x110
	s_cmp_lt_u32 s85, 26
	v_mad_u32_u24 v229, v227, s35, v214
	s_cselect_b64 s[50:51], -1, 0
	s_lshl_b32 s35, s85, 10
	s_cmp_lt_u32 s6, 26
	s_cselect_b64 s[54:55], -1, 0
	s_lshl_b32 s44, s6, 10
	s_cmp_lt_u32 s7, 26
	s_cselect_b64 s[58:59], -1, 0
	s_lshl_b32 s45, s7, 10
	s_cmp_lt_u32 s14, 26
	s_cselect_b64 s[6:7], -1, 0
	s_lshl_b32 s46, s14, 10
	s_cmp_lt_u32 s15, 26
	s_cselect_b64 s[66:67], -1, 0
	s_lshl_b32 s47, s15, 10
	s_cmp_lt_u32 s33, 26
	s_cselect_b64 s[14:15], -1, 0
	s_lshl_b32 s33, s33, 10
	s_add_i32 s88, s35, 0
	s_add_i32 s90, s44, 0
	s_add_i32 s91, s45, 0
	s_add_i32 s92, s46, 0
	s_add_i32 s93, s47, 0
	s_add_i32 s94, s33, 0
	s_and_b64 s[44:45], s[50:51], exec
	s_cselect_b32 s33, s73, s37
	s_cselect_b32 s35, s74, s38
	s_cmp_lt_i32 s85, 26
	s_cselect_b64 s[44:45], -1, 0
	s_and_b64 s[46:47], s[48:49], exec
	s_cselect_b32 s47, s9, s35
	s_cselect_b32 s46, s8, s33
	s_and_b64 s[50:51], s[50:51], exec
	s_cselect_b32 s33, 13, 7
	s_and_b64 s[48:49], s[48:49], exec
	s_cselect_b32 s95, 18, s33
	s_and_b64 s[48:49], s[54:55], exec
	s_cselect_b32 s33, s73, s37
	s_cselect_b32 s35, s74, s38
	s_cmp_lt_i32 s85, 18
	s_cselect_b64 s[48:49], -1, 0
	s_and_b64 s[50:51], exec, s[52:53]
	s_cselect_b32 s51, s9, s35
	s_cselect_b32 s50, s8, s33
	s_and_b64 s[54:55], s[54:55], exec
	s_cselect_b32 s33, 13, 7
	s_and_b64 s[52:53], exec, s[52:53]
	s_cselect_b32 s96, 18, s33
	s_and_b64 s[52:53], s[58:59], exec
	s_cselect_b32 s33, s73, s37
	s_cselect_b32 s35, s74, s38
	s_cmp_lt_i32 s85, 10
	s_cselect_b64 s[52:53], -1, 0
	s_and_b64 s[54:55], exec, s[56:57]
	s_cselect_b32 s55, s9, s35
	s_cselect_b32 s54, s8, s33
	s_and_b64 s[58:59], s[58:59], exec
	s_cselect_b32 s33, 13, 7
	s_and_b64 s[56:57], exec, s[56:57]
	s_cselect_b32 s97, 18, s33
	s_and_b64 s[56:57], s[6:7], exec
	s_cselect_b32 s33, s73, s37
	s_cselect_b32 s35, s74, s38
	s_cmp_lt_i32 s85, 2
	s_cselect_b64 s[56:57], -1, 0
	s_and_b64 s[58:59], exec, s[60:61]
	s_cselect_b32 s59, s9, s35
	s_cselect_b32 s58, s8, s33
	s_and_b64 s[6:7], s[6:7], exec
	v_add_u32_e32 v230, 0, v229
	s_cselect_b32 s33, 13, 7
	s_and_b64 s[6:7], exec, s[60:61]
	s_waitcnt vmcnt(0)
	ds_write_b128 v1, v[2:5]
	ds_write_b128 v1, v[6:9] offset:32
	ds_write_b128 v1, v[10:13] offset:64
	ds_write_b128 v1, v[14:17] offset:96
	s_waitcnt vmcnt(0) lgkmcnt(0)
	s_barrier
	ds_read_b128 v[112:115], v1
	ds_read_b128 v[116:119], v1 offset:32
	ds_read_b128 v[120:123], v1 offset:64
	ds_read_b128 v[124:127], v1 offset:96
	ds_read_b128 v[168:171], v230
	ds_read_b128 v[160:163], v230 offset:32
	ds_read_b128 v[164:167], v230 offset:64
	ds_read_b128 v[152:155], v230 offset:96
	ds_read_b128 v[156:159], v230 offset:128
	ds_read_b128 v[128:131], v230 offset:160
	ds_read_b128 v[132:135], v230 offset:192
	ds_read_b128 v[136:139], v230 offset:224
	s_cselect_b32 s6, 18, s33
	s_and_b64 s[60:61], s[66:67], exec
	v_lshlrev_b32_e32 v1, 7, v227
	s_cselect_b32 s7, s73, s37
	s_cselect_b32 s33, s74, s38
	s_cmp_lt_i32 s85, -6
	v_sub_u32_e32 v1, v229, v1
	s_cselect_b64 s[60:61], -1, 0
	s_and_b64 s[62:63], exec, s[64:65]
	v_add_u32_e32 v231, 0, v1
	s_cselect_b32 s63, s9, s33
	s_cselect_b32 s62, s8, s7
	s_and_b64 s[66:67], s[66:67], exec
	ds_read_b128 v[140:143], v231 offset:17408
	ds_read_b128 v[144:147], v231 offset:17440
	ds_read_b128 v[148:151], v231 offset:17472
	ds_read_b128 v[208:211], v231 offset:17504
	s_cselect_b32 s7, 13, 7
	s_and_b64 s[64:65], exec, s[64:65]
	s_cselect_b32 s7, 18, s7
	s_and_b64 s[64:65], s[14:15], exec
	s_cselect_b32 s33, s73, s37
	s_cselect_b32 s35, s74, s38
	s_cmp_lt_i32 s85, -14
	s_cselect_b64 s[64:65], -1, 0
	s_and_b64 s[66:67], exec, s[68:69]
	v_mul_u32_u24_e32 v2, 0x90, v227
	s_cselect_b32 s67, s9, s35
	s_cselect_b32 s66, s8, s33
	s_and_b64 s[14:15], s[14:15], exec
	v_mov_b32_e32 v14, v215
	v_mov_b32_e32 v15, v215
	v_lshlrev_b32_e32 v232, 2, v0
	s_cselect_b32 s33, 13, 7
	s_and_b64 s[14:15], exec, s[68:69]
	v_add_u32_e32 v233, v2, v214
	v_mov_b32_e32 v0, v215
	v_mov_b32_e32 v1, v215
	v_mov_b32_e32 v2, v215
	v_mov_b32_e32 v3, v215
	v_mov_b32_e32 v4, v215
	v_mov_b32_e32 v5, v215
	v_mov_b32_e32 v6, v215
	v_mov_b32_e32 v7, v215
	v_mov_b32_e32 v8, v215
	v_mov_b32_e32 v9, v215
	v_mov_b32_e32 v10, v215
	v_mov_b32_e32 v11, v215
	v_mov_b32_e32 v12, v215
	v_mov_b32_e32 v13, v215
	v_mov_b64_e32 v[30:31], v[14:15]
	v_mov_b64_e32 v[46:47], v[14:15]
	v_mov_b64_e32 v[62:63], v[14:15]
	s_cselect_b32 s33, 18, s33
	v_add_u32_e32 v234, 0, v233
	s_add_i32 s14, s34, 0x100
	s_mov_b32 s15, 0
	v_mov_b32_e32 v235, 0
	v_mov_b32_e32 v236, 0
	v_mov_b32_e32 v238, 0
	v_mov_b32_e32 v239, 0
	v_mov_b32_e32 v240, 0
	v_mov_b32_e32 v241, 0
	v_mov_b32_e32 v242, 0
	v_mov_b32_e32 v243, 0
	v_mov_b32_e32 v244, 0
	v_mov_b32_e32 v245, 0
	v_mov_b32_e32 v246, 0
	v_mov_b32_e32 v247, 0
	v_mov_b32_e32 v248, 0
	v_mov_b32_e32 v249, 0
	v_mov_b32_e32 v250, 0
	v_mov_b32_e32 v251, 0
	v_mov_b32_e32 v252, 0
	v_mov_b32_e32 v253, 0
	v_mov_b64_e32 v[28:29], v[12:13]
	v_mov_b64_e32 v[26:27], v[10:11]
	v_mov_b64_e32 v[24:25], v[8:9]
	v_mov_b64_e32 v[22:23], v[6:7]
	v_mov_b64_e32 v[20:21], v[4:5]
	v_mov_b64_e32 v[18:19], v[2:3]
	v_mov_b64_e32 v[16:17], v[0:1]
	v_mov_b64_e32 v[44:45], v[12:13]
	v_mov_b64_e32 v[42:43], v[10:11]
	v_mov_b64_e32 v[40:41], v[8:9]
	v_mov_b64_e32 v[38:39], v[6:7]
	v_mov_b64_e32 v[36:37], v[4:5]
	v_mov_b64_e32 v[34:35], v[2:3]
	v_mov_b64_e32 v[32:33], v[0:1]
	v_mov_b64_e32 v[60:61], v[12:13]
	v_mov_b64_e32 v[58:59], v[10:11]
	v_mov_b64_e32 v[56:57], v[8:9]
	v_mov_b64_e32 v[54:55], v[6:7]
	v_mov_b64_e32 v[52:53], v[4:5]
	v_mov_b64_e32 v[50:51], v[2:3]
	v_mov_b64_e32 v[48:49], v[0:1]
	s_mov_b32 s35, 0
	s_and_b32 s45, s85, 3
	s_lshl_b32 s44, s45, 10
	s_mov_b32 s52, s73
	s_mov_b32 s53, s74
	s_mov_b32 s54, s37
	s_mov_b32 s55, s38
	s_cmp_ge_u32 s85, 4
	s_cbranch_scc1 .Lxd_sy
	s_add_i32 s18, s45, 0
	s_lshl_b32 s18, s18, 10
	v_lshl_add_u32 v72, v219, 4, s18
	s_mov_b32 s19, 15790321
	v_mul_hi_u32 v73, v72, s19
	v_mul_u32_u24_e32 v74, 272, v73
	v_sub_u32_e32 v74, v72, v74
	v_min_u32_e32 v74, 240, v74
	v_lshlrev_b32_e32 v75, 12, v73
	v_add3_u32 v221, v75, v74, s84
	s_add_i32 s18, s45, 4
	s_lshl_b32 s18, s18, 10
	v_lshl_add_u32 v72, v219, 4, s18
	s_mov_b32 s19, 15790321
	v_mul_hi_u32 v73, v72, s19
	v_mul_u32_u24_e32 v74, 272, v73
	v_sub_u32_e32 v74, v72, v74
	v_min_u32_e32 v74, 240, v74
	v_lshlrev_b32_e32 v75, 12, v73
	v_add3_u32 v222, v75, v74, s84
	s_add_i32 s18, s45, 8
	s_lshl_b32 s18, s18, 10
	v_lshl_add_u32 v72, v219, 4, s18
	s_mov_b32 s19, 15790321
	v_mul_hi_u32 v73, v72, s19
	v_mul_u32_u24_e32 v74, 272, v73
	v_sub_u32_e32 v74, v72, v74
	v_min_u32_e32 v74, 240, v74
	v_lshlrev_b32_e32 v75, 12, v73
	v_add3_u32 v223, v75, v74, s84
	s_add_i32 s18, s45, 12
	s_lshl_b32 s18, s18, 10
	v_lshl_add_u32 v72, v219, 4, s18
	s_mov_b32 s19, 15790321
	v_mul_hi_u32 v73, v72, s19
	v_mul_u32_u24_e32 v74, 272, v73
	v_sub_u32_e32 v74, v72, v74
	v_min_u32_e32 v74, 240, v74
	v_lshlrev_b32_e32 v75, 12, v73
	v_add3_u32 v224, v75, v74, s84
	s_cmp_ge_u32 s45, 1
	s_cselect_b32 s18, -1, 16
	s_mov_b32 s24, 29826162
	s_mov_b32 s25, 15790321
	s_cselect_b32 s19, s24, s25
	s_mov_b32 s24, 144
	s_mov_b32 s25, 272
	s_cselect_b32 s20, s24, s25
	s_mov_b32 s24, 112
	s_mov_b32 s25, 240
	s_cselect_b32 s21, s24, s25
	s_cselect_b32 s22, 7, 12
	s_cselect_b32 s23, 0, s84
	s_add_i32 s18, s45, s18
	s_lshl_b32 s18, s18, 10
	v_lshl_add_u32 v72, v219, 4, s18
	v_mul_hi_u32 v73, v72, s19
	v_mul_lo_u32 v74, v73, s20
	v_sub_u32_e32 v74, v72, v74
	v_min_u32_e32 v74, s21, v74
	v_lshlrev_b32_e32 v75, s22, v73
	v_add3_u32 v225, v75, v74, s23
	s_add_i32 s18, s45, 3
	s_lshl_b32 s18, s18, 10
	v_lshl_add_u32 v72, v219, 4, s18
	s_mov_b32 s19, 29826162
	v_mul_hi_u32 v73, v72, s19
	v_mul_u32_u24_e32 v74, 144, v73
	v_sub_u32_e32 v74, v72, v74
	v_min_u32_e32 v74, 112, v74
	v_lshlrev_b32_e32 v75, 7, v73
	v_add_u32_e32 v226, v75, v74
	s_cmp_ge_u32 s45, 1
	s_cselect_b32 s95, 13, 18
	s_cselect_b32 s46, s73, s8
	s_cselect_b32 s47, s74, s9
	s_branch .Lxd_sdone
